# E1 plus removal of the redundant cooperative-groups grid sync at startup (the kernel's own chip barrier follows immediately)
# speedup vs baseline: 1.0017x; 1.0017x over previous
; #define CHIP_BAR(k) { PH_BEGIN grid_bar((unsigned*)(ws + O_BAR) + 64 * 8, (unsigned)(k) * (unsigned)G, tid); }
; DI void grid_bar(unsigned* ctr, unsigned target, int tid) {
;     asm volatile("s_waitcnt vmcnt(0)" ::: "memory");
;     __syncthreads();
;     if (tid == 0) {
;         __builtin_amdgcn_fence(__ATOMIC_RELEASE, "agent");
;         asm volatile("s_waitcnt vmcnt(0)" ::: "memory");
;         __hip_atomic_fetch_add(ctr, 1u, __ATOMIC_RELAXED, __HIP_MEMORY_SCOPE_AGENT);
;         while (__hip_atomic_load(ctr, __ATOMIC_RELAXED, __HIP_MEMORY_SCOPE_AGENT) < target) __builtin_amdgcn_s_sleep(1);
;         __builtin_amdgcn_fence(__ATOMIC_ACQUIRE, "agent");
;         asm volatile("s_waitcnt vmcnt(0)" ::: "memory");
;     }
;     __syncthreads();
; }
; __global__ void __launch_bounds__(NTHREADS, 2) hybrid_fwd(Args A_unused) {
;     ...
;     cg::this_grid().sync();
;     CHIP_BAR(1)
.LBB0_126:
	s_or_b64 exec, exec, s[6:7]
	s_mov_b64 s[2:3], s[76:77]
	s_mov_b32 s0, s75
	v_mov_b32_e32 v0, 0
	s_waitcnt vmcnt(0)
	s_lshl_b32 s0, s0, 6
	v_mbcnt_lo_u32_b32 v0, -1, v0
	v_mbcnt_hi_u32_b32 v0, -1, v0
	v_sub_u32_e32 v0, 0, v0
	v_cmp_eq_u32_e32 vcc, s0, v0
	s_barrier
	s_and_saveexec_b64 s[0:1], vcc
	s_cbranch_execz .LBB0_142
	s_load_dwordx2 s[2:3], s[2:3], 0xf0
	s_mov_b64 s[4:5], exec
	buffer_wbl2 sc1
	s_waitcnt vmcnt(0) lgkmcnt(0)
	s_waitcnt vmcnt(0)
	v_mbcnt_lo_u32_b32 v0, s4, 0
	s_add_u32 s2, s2, 0x3f400800
	v_mbcnt_hi_u32_b32 v0, s5, v0
	s_addc_u32 s3, s3, 0
	v_cmp_eq_u32_e32 vcc, 0, v0
	s_and_saveexec_b64 s[6:7], vcc
	s_cbranch_execz .LBB0_139
	s_bcnt1_i32_b64 s4, s[4:5]
	v_mov_b32_e32 v0, 0
	v_mov_b32_e32 v1, s4
	global_atomic_add v0, v1, s[2:3]
